# RWKV prefetch blocks: row pointer increments and immediate offsets instead of per-load 64-bit address rebuilds
# baseline (speedup 1.0000x reference)
.LBB0_334:
	v_lshlrev_b32_e32 v9, 16, v9
	v_mul_f32_e32 v9, 0x3fb8aa3b, v9
	v_lshlrev_b32_e32 v8, 16, v62
	v_lshlrev_b32_e32 v62, 16, v88
	v_lshlrev_b32_e32 v63, 16, v67
	v_exp_f32_e32 v9, v9
	v_lshlrev_b32_e32 v20, 16, v20
	v_sub_f32_e32 v63, v63, v62
	v_add_f32_e32 v67, -1.0, v20
	v_fma_f32 v63, v16, v63, v62
	v_fma_f32 v67, v19, v67, 1.0
	v_lshlrev_b32_e32 v65, 16, v68
	v_lshlrev_b32_e32 v66, 16, v66
	v_mul_f32_e32 v67, v67, v63
	v_sub_f32_e32 v66, v66, v65
	ds_write2st64_b32 v32, v9, v67 offset0:16 offset1:32
	v_mul_f32_e64 v9, v18, -v63
	v_fma_f32 v66, v17, v66, v65
	v_mul_f32_e32 v9, v21, v9
	v_lshlrev_b32_e32 v22, 16, v22
	v_lshlrev_b32_e32 v0, 16, v89
	ds_write2st64_b32 v32, v66, v9 offset0:48 offset1:64
	v_mul_f32_e64 v9, -v9, v20
	v_mul_f32_e32 v22, 0x3fb8aa3b, v22
	v_sub_f32_e32 v8, v8, v0
	ds_write_b32 v32, v9 offset:20480
	v_lshlrev_b32_e32 v9, 16, v61
	v_lshlrev_b32_e32 v20, 16, v57
	v_exp_f32_e32 v22, v22
	v_lshlrev_b32_e32 v23, 16, v23
	v_fma_f32 v8, v3, v8, v0
	v_lshlrev_b32_e32 v21, 16, v58
	v_sub_f32_e32 v0, v0, v9
	v_sub_f32_e32 v57, v62, v20
	v_add_f32_e32 v61, -1.0, v23
	v_fma_f32 v0, v3, v0, v9
	v_fma_f32 v57, v16, v57, v20
	v_sub_f32_e32 v58, v65, v21
	v_fma_f32 v61, v19, v61, 1.0
	v_fma_f32 v58, v17, v58, v21
	v_mul_f32_e32 v61, v61, v57
	ds_write2st64_b32 v32, v8, v0 offset1:1
	ds_write_b32 v33, v22 offset:256
	ds_write_b32 v34, v61 offset:256
	ds_write_b32 v35, v58 offset:256
	v_mul_f32_e64 v0, v18, -v57
	v_mul_f32_e32 v0, v24, v0
	ds_write_b32 v36, v0 offset:256
	v_mul_f32_e64 v0, -v0, v23
	v_lshlrev_b32_e32 v23, 16, v25
	v_mul_f32_e32 v23, 0x3fb8aa3b, v23
	ds_write_b32 v37, v0 offset:256
	v_lshlrev_b32_e32 v0, 16, v64
	v_lshlrev_b32_e32 v8, 16, v60
	v_exp_f32_e32 v23, v23
	v_lshlrev_b32_e32 v24, 16, v27
	v_lshlrev_b32_e32 v22, 16, v56
	v_sub_f32_e32 v9, v9, v0
	v_sub_f32_e32 v20, v20, v8
	v_add_f32_e32 v25, -1.0, v24
	v_fma_f32 v9, v3, v9, v0
	v_fma_f32 v20, v16, v20, v8
	v_sub_f32_e32 v21, v21, v22
	v_fma_f32 v25, v19, v25, 1.0
	v_fma_f32 v21, v17, v21, v22
	v_mul_f32_e32 v25, v25, v20
	ds_write_b32 v32, v9 offset:512
	ds_write_b32 v33, v23 offset:512
	ds_write_b32 v34, v25 offset:512
	ds_write_b32 v35, v21 offset:512
	v_mul_f32_e64 v9, v18, -v20
	v_mul_f32_e32 v9, v26, v9
	ds_write_b32 v36, v9 offset:512
	v_mul_f32_e64 v9, -v9, v24
	ds_write_b32 v37, v9 offset:512
	v_lshlrev_b32_e32 v9, 16, v55
	v_lshlrev_b32_e32 v20, 16, v59
	v_sub_f32_e32 v0, v0, v9
	v_lshlrev_b32_e32 v21, 16, v54
	v_fmac_f32_e32 v9, v3, v0
	v_sub_f32_e32 v0, v8, v20
	v_fmac_f32_e32 v20, v16, v0
	v_sub_f32_e32 v0, v22, v21
	v_fmac_f32_e32 v21, v17, v0
	v_lshlrev_b32_e32 v0, 16, v28
	v_mul_f32_e32 v0, 0x3fb8aa3b, v0
	v_exp_f32_e32 v0, v0
	v_lshlrev_b32_e32 v8, 16, v29
	v_add_f32_e32 v22, -1.0, v8
	v_fma_f32 v22, v19, v22, 1.0
	v_mul_f32_e32 v22, v22, v20
	ds_write_b32 v32, v9 offset:768
	ds_write_b32 v33, v0 offset:768
	ds_write_b32 v34, v22 offset:768
	ds_write_b32 v35, v21 offset:768
	v_mul_f32_e64 v0, v18, -v20
	v_mul_f32_e32 v0, v30, v0
	s_min_u32 s5, s4, 0xfd
	ds_write_b32 v36, v0 offset:768
	v_mul_f32_e64 v0, -v0, v8
	v_lshl_add_u32 v8, s5, 4, v38
	ds_write_b32 v37, v0 offset:768
	v_max_i32_e32 v0, 1, v8
	v_add_u32_e32 v0, -1, v0
	v_lshl_add_u64 v[20:21], s[56:57], 0, v[0:1]
	v_mad_u64_u32 v[22:23], s[6:7], v20, s29, v[4:5]
	v_max_i32_e32 v0, 0, v8
	v_mad_i32_i24 v23, v21, s29, v23
	v_lshl_add_u64 v[20:21], s[56:57], 0, v[0:1]
	v_max_i32_e32 v0, -1, v8
	s_waitcnt lgkmcnt(0)
	s_barrier
	ds_read_b128 v[220:223], v40 offset:16384
	ds_read_b128 v[236:239], v40 offset:8192
	ds_read2st64_b32 v[108:109], v39 offset0:0 offset1:1
	ds_read_b128 v[244:247], v40 offset:20480
	ds_read_b128 v[228:231], v40 offset:4096
	ds_read_b128 v[100:103], v40 offset:0
	ds_read_b128 v[224:227], v40 offset:16640
	ds_read_b128 v[240:243], v40 offset:8448
	ds_read2st64_b32 v[110:111], v39 offset0:2 offset1:3
	ds_read_b128 v[248:251], v40 offset:20736
	ds_read_b128 v[232:235], v40 offset:4352
	s_mov_b64 s[6:7], 0xd00
	global_load_ushort v55, v[22:23], off
	global_load_ushort v57, v[22:23], off offset:1024
	global_load_ushort v54, v[22:23], off offset:2048
	v_lshl_add_u64 v[112:113], v[22:23], 0, s[6:7]
	global_load_ushort v59, v[112:113], off
	global_load_ushort v60, v[112:113], off offset:1024
	global_load_ushort v56, v[112:113], off offset:2048
	v_lshl_add_u64 v[114:115], v[112:113], 0, s[6:7]
	global_load_ushort v61, v[114:115], off
	global_load_ushort v62, v[114:115], off offset:1024
	global_load_ushort v58, v[114:115], off offset:2048
	v_lshl_add_u64 v[116:117], v[114:115], 0, s[6:7]
	global_load_ushort v64, v[116:117], off
	global_load_ushort v67, v[116:117], off offset:1024
	global_load_ushort v63, v[116:117], off offset:2048
	v_lshl_add_u64 v[118:119], v[116:117], 0, s[6:7]
	v_ashrrev_i32_e32 v9, 31, v8
	v_lshl_add_u64 v[120:121], s[56:57], 0, v[8:9]
	v_lshlrev_b32_e32 v83, 1, v2
	v_lshlrev_b64 v[122:123], 10, v[120:121]
	v_or_b32_e32 v122, v122, v83
	v_lshl_add_u64 v[124:125], s[0:1], 0, v[122:123]
	v_lshl_add_u64 v[126:127], s[24:25], 0, v[122:123]
	v_lshlrev_b64 v[128:129], 5, v[120:121]
	v_lshl_add_u64 v[128:129], s[58:59], 0, v[128:129]
	global_load_ushort v66, v[118:119], off
	global_load_ushort v68, v[118:119], off offset:1024
	global_load_ushort v65, v[118:119], off offset:2048
	global_load_ushort v9, v[124:125], off
	global_load_dword v24, v[128:129], off offset:32
	global_load_ushort v20, v[126:127], off
	global_load_dword v21, v[128:129], off
	global_load_ushort v22, v[124:125], off offset:1024
	global_load_ushort v23, v[126:127], off offset:1024
	global_load_ushort v25, v[124:125], off offset:2048
	global_load_ushort v27, v[126:127], off offset:2048
	global_load_dword v30, v[128:129], off offset:96
	global_load_dword v26, v[128:129], off offset:64
	global_load_ushort v28, v[124:125], off offset:3072
	global_load_ushort v29, v[126:127], off offset:3072
	v_mov_b32_e32 v0, v31
	v_mov_b32_e32 v84, v40
	v_mov_b32_e32 v86, 0
	v_mov_b32_e32 v85, v39
	s_mov_b32 s5, 0
	s_waitcnt lgkmcnt(6)
	v_pk_mul_f32 v[88:89], v[12:13], v[220:221]
	v_pk_fma_f32 v[88:89], v[10:11], v[222:223], v[88:89]
	v_add_f32_e32 v90, v88, v89
	v_pk_mul_f32 v[92:93], v[108:109], v[236:237] op_sel_hi:[0,1]
	v_pk_mul_f32 v[94:95], v[108:109], v[238:239] op_sel_hi:[0,1]
	v_add_f32_dpp v90, v90, v90 row_ror:8 row_mask:0xf bank_mask:0xf bound_ctrl:1
	ds_read_b128 v[220:223], v40 offset:16896
	ds_read_b128 v[236:239], v40 offset:8704
	v_add_f32_dpp v90, v90, v90 row_ror:4 row_mask:0xf bank_mask:0xf bound_ctrl:1
	s_nop 1
	v_add_f32_dpp v90, v90, v90 row_ror:2 row_mask:0xf bank_mask:0xf bound_ctrl:1
	ds_read_b128 v[104:107], v40 offset:256
	s_nop 0
	v_add_f32_dpp v90, v90, v90 row_ror:1 row_mask:0xf bank_mask:0xf bound_ctrl:1
	v_pk_fma_f32 v[92:93], v[90:91], v[244:245], v[92:93] op_sel_hi:[0,1,1]
	v_pk_fma_f32 v[94:95], v[90:91], v[246:247], v[94:95] op_sel_hi:[0,1,1]
	ds_read_b128 v[244:247], v40 offset:20992
	v_pk_fma_f32 v[12:13], v[12:13], v[228:229], v[92:93]
	v_pk_fma_f32 v[10:11], v[10:11], v[230:231], v[94:95]
	ds_read_b128 v[228:231], v40 offset:4608
	s_waitcnt lgkmcnt(5)
	v_pk_mul_f32 v[88:89], v[12:13], v[224:225]
	v_pk_fma_f32 v[88:89], v[10:11], v[226:227], v[88:89]
	v_add_f32_e32 v90, v88, v89
	v_pk_mul_f32 v[92:93], v[108:109], v[240:241] op_sel:[1,0] op_sel_hi:[1,1]
	v_pk_mul_f32 v[94:95], v[108:109], v[242:243] op_sel:[1,0] op_sel_hi:[1,1]
	v_add_f32_dpp v90, v90, v90 row_ror:8 row_mask:0xf bank_mask:0xf bound_ctrl:1
	ds_read_b128 v[224:227], v40 offset:17152
	ds_read_b128 v[240:243], v40 offset:8960
	v_add_f32_dpp v90, v90, v90 row_ror:4 row_mask:0xf bank_mask:0xf bound_ctrl:1
	v_pk_mul_f32 v[100:101], v[12:13], v[100:101]
	v_pk_fma_f32 v[100:101], v[10:11], v[102:103], v[100:101]
	v_add_f32_dpp v90, v90, v90 row_ror:2 row_mask:0xf bank_mask:0xf bound_ctrl:1
	v_add_f32_e32 v96, v100, v101
	ds_read_b128 v[100:103], v40 offset:512
	v_add_f32_dpp v90, v90, v90 row_ror:1 row_mask:0xf bank_mask:0xf bound_ctrl:1
	ds_read2st64_b32 v[108:109], v39 offset0:4 offset1:5
	v_pk_fma_f32 v[92:93], v[90:91], v[248:249], v[92:93] op_sel_hi:[0,1,1]
	v_pk_fma_f32 v[94:95], v[90:91], v[250:251], v[94:95] op_sel_hi:[0,1,1]
	ds_read_b128 v[248:251], v40 offset:21248
	v_pk_fma_f32 v[12:13], v[12:13], v[232:233], v[92:93]
	v_pk_fma_f32 v[10:11], v[10:11], v[234:235], v[94:95]
	ds_read_b128 v[232:235], v40 offset:4864
	s_waitcnt lgkmcnt(6)
	v_pk_mul_f32 v[88:89], v[12:13], v[220:221]
	v_pk_fma_f32 v[88:89], v[10:11], v[222:223], v[88:89]
	v_add_f32_e32 v90, v88, v89
	v_pk_mul_f32 v[92:93], v[110:111], v[236:237] op_sel_hi:[0,1]
	v_pk_mul_f32 v[94:95], v[110:111], v[238:239] op_sel_hi:[0,1]
	v_add_f32_dpp v90, v90, v90 row_ror:8 row_mask:0xf bank_mask:0xf bound_ctrl:1
	ds_read_b128 v[220:223], v40 offset:17408
	ds_read_b128 v[236:239], v40 offset:9216
	v_add_f32_dpp v90, v90, v90 row_ror:4 row_mask:0xf bank_mask:0xf bound_ctrl:1
	v_pk_mul_f32 v[104:105], v[12:13], v[104:105]
	v_pk_fma_f32 v[104:105], v[10:11], v[106:107], v[104:105]
	v_add_f32_dpp v90, v90, v90 row_ror:2 row_mask:0xf bank_mask:0xf bound_ctrl:1
	v_add_f32_e32 v97, v104, v105
	ds_read_b128 v[104:107], v40 offset:768
	v_add_f32_dpp v90, v90, v90 row_ror:1 row_mask:0xf bank_mask:0xf bound_ctrl:1
	v_pk_fma_f32 v[92:93], v[90:91], v[244:245], v[92:93] op_sel_hi:[0,1,1]
	v_pk_fma_f32 v[94:95], v[90:91], v[246:247], v[94:95] op_sel_hi:[0,1,1]
	ds_read_b128 v[244:247], v40 offset:21504
	v_pk_fma_f32 v[12:13], v[12:13], v[228:229], v[92:93]
	v_pk_fma_f32 v[10:11], v[10:11], v[230:231], v[94:95]
	ds_read_b128 v[228:231], v40 offset:5120
	s_waitcnt lgkmcnt(5)
	v_pk_mul_f32 v[88:89], v[12:13], v[224:225]
	v_pk_fma_f32 v[88:89], v[10:11], v[226:227], v[88:89]
	v_add_f32_e32 v90, v88, v89
	v_pk_mul_f32 v[92:93], v[110:111], v[240:241] op_sel:[1,0] op_sel_hi:[1,1]
	v_pk_mul_f32 v[94:95], v[110:111], v[242:243] op_sel:[1,0] op_sel_hi:[1,1]
	v_add_f32_dpp v90, v90, v90 row_ror:8 row_mask:0xf bank_mask:0xf bound_ctrl:1
	ds_read_b128 v[224:227], v40 offset:17664
	ds_read_b128 v[240:243], v40 offset:9472
	v_add_f32_dpp v90, v90, v90 row_ror:4 row_mask:0xf bank_mask:0xf bound_ctrl:1
	v_pk_mul_f32 v[100:101], v[12:13], v[100:101]
	v_pk_fma_f32 v[100:101], v[10:11], v[102:103], v[100:101]
	v_add_f32_dpp v90, v90, v90 row_ror:2 row_mask:0xf bank_mask:0xf bound_ctrl:1
	v_add_f32_e32 v98, v100, v101
	ds_read_b128 v[100:103], v40 offset:1024
	v_add_f32_dpp v90, v90, v90 row_ror:1 row_mask:0xf bank_mask:0xf bound_ctrl:1
	ds_read2st64_b32 v[110:111], v39 offset0:6 offset1:7
	v_pk_fma_f32 v[92:93], v[90:91], v[248:249], v[92:93] op_sel_hi:[0,1,1]
	v_pk_fma_f32 v[94:95], v[90:91], v[250:251], v[94:95] op_sel_hi:[0,1,1]
	ds_read_b128 v[248:251], v40 offset:21760
	v_pk_fma_f32 v[12:13], v[12:13], v[232:233], v[92:93]
	v_pk_fma_f32 v[10:11], v[10:11], v[234:235], v[94:95]
	ds_read_b128 v[232:235], v40 offset:5376
	s_waitcnt lgkmcnt(6)
	v_pk_mul_f32 v[88:89], v[12:13], v[220:221]
	v_pk_fma_f32 v[88:89], v[10:11], v[222:223], v[88:89]
	v_add_f32_e32 v90, v88, v89
	v_pk_mul_f32 v[92:93], v[108:109], v[236:237] op_sel_hi:[0,1]
	v_pk_mul_f32 v[94:95], v[108:109], v[238:239] op_sel_hi:[0,1]
	v_add_f32_dpp v90, v90, v90 row_ror:8 row_mask:0xf bank_mask:0xf bound_ctrl:1
	ds_read_b128 v[220:223], v40 offset:17920
	ds_read_b128 v[236:239], v40 offset:9728
	v_add_f32_dpp v90, v90, v90 row_ror:4 row_mask:0xf bank_mask:0xf bound_ctrl:1
	v_pk_mul_f32 v[104:105], v[12:13], v[104:105]
	v_pk_fma_f32 v[104:105], v[10:11], v[106:107], v[104:105]
	v_add_f32_dpp v90, v90, v90 row_ror:2 row_mask:0xf bank_mask:0xf bound_ctrl:1
	v_add_f32_e32 v99, v104, v105
	ds_read_b128 v[104:107], v40 offset:1280
	v_add_f32_dpp v90, v90, v90 row_ror:1 row_mask:0xf bank_mask:0xf bound_ctrl:1
	v_pk_fma_f32 v[92:93], v[90:91], v[244:245], v[92:93] op_sel_hi:[0,1,1]
	v_pk_fma_f32 v[94:95], v[90:91], v[246:247], v[94:95] op_sel_hi:[0,1,1]
	ds_read_b128 v[244:247], v40 offset:22016
	v_pk_fma_f32 v[12:13], v[12:13], v[228:229], v[92:93]
	v_pk_fma_f32 v[10:11], v[10:11], v[230:231], v[94:95]
	ds_read_b128 v[228:231], v40 offset:5632
	s_waitcnt lgkmcnt(5)
	v_pk_mul_f32 v[88:89], v[12:13], v[224:225]
	v_pk_fma_f32 v[88:89], v[10:11], v[226:227], v[88:89]
	v_add_f32_e32 v90, v88, v89
	v_pk_mul_f32 v[92:93], v[108:109], v[240:241] op_sel:[1,0] op_sel_hi:[1,1]
	v_pk_mul_f32 v[94:95], v[108:109], v[242:243] op_sel:[1,0] op_sel_hi:[1,1]
	v_add_f32_dpp v90, v90, v90 row_ror:8 row_mask:0xf bank_mask:0xf bound_ctrl:1
	ds_read_b128 v[224:227], v40 offset:18176
	ds_read_b128 v[240:243], v40 offset:9984
	v_add_f32_dpp v90, v90, v90 row_ror:4 row_mask:0xf bank_mask:0xf bound_ctrl:1
	v_pk_mul_f32 v[100:101], v[12:13], v[100:101]
	v_pk_fma_f32 v[100:101], v[10:11], v[102:103], v[100:101]
	v_add_f32_dpp v90, v90, v90 row_ror:2 row_mask:0xf bank_mask:0xf bound_ctrl:1
	v_add_f32_e32 v87, v100, v101
	ds_read_b128 v[100:103], v40 offset:1536
	v_add_f32_dpp v90, v90, v90 row_ror:1 row_mask:0xf bank_mask:0xf bound_ctrl:1
	ds_read2st64_b32 v[108:109], v39 offset0:8 offset1:9
	v_pk_fma_f32 v[92:93], v[90:91], v[248:249], v[92:93] op_sel_hi:[0,1,1]
	v_pk_fma_f32 v[94:95], v[90:91], v[250:251], v[94:95] op_sel_hi:[0,1,1]
	ds_read_b128 v[248:251], v40 offset:22272
	v_pk_fma_f32 v[12:13], v[12:13], v[232:233], v[92:93]
	v_pk_fma_f32 v[10:11], v[10:11], v[234:235], v[94:95]
	ds_read_b128 v[232:235], v40 offset:5888
	s_waitcnt lgkmcnt(6)
	v_pk_mul_f32 v[88:89], v[12:13], v[220:221]
	v_pk_fma_f32 v[88:89], v[10:11], v[222:223], v[88:89]
	v_add_f32_e32 v90, v88, v89
	v_pk_mul_f32 v[92:93], v[110:111], v[236:237] op_sel_hi:[0,1]
	v_pk_mul_f32 v[94:95], v[110:111], v[238:239] op_sel_hi:[0,1]
	v_add_f32_dpp v90, v90, v90 row_ror:8 row_mask:0xf bank_mask:0xf bound_ctrl:1
	ds_read_b128 v[220:223], v40 offset:18432
	ds_read_b128 v[236:239], v40 offset:10240
	v_add_f32_dpp v90, v90, v90 row_ror:4 row_mask:0xf bank_mask:0xf bound_ctrl:1
	v_pk_mul_f32 v[104:105], v[12:13], v[104:105]
	v_pk_fma_f32 v[104:105], v[10:11], v[106:107], v[104:105]
	v_add_f32_dpp v90, v90, v90 row_ror:2 row_mask:0xf bank_mask:0xf bound_ctrl:1
	v_add_f32_e32 v217, v104, v105
	ds_read_b128 v[104:107], v40 offset:1792
	v_add_f32_dpp v90, v90, v90 row_ror:1 row_mask:0xf bank_mask:0xf bound_ctrl:1
	v_pk_fma_f32 v[92:93], v[90:91], v[244:245], v[92:93] op_sel_hi:[0,1,1]
	v_pk_fma_f32 v[94:95], v[90:91], v[246:247], v[94:95] op_sel_hi:[0,1,1]
	ds_read_b128 v[244:247], v40 offset:22528
	v_pk_fma_f32 v[12:13], v[12:13], v[228:229], v[92:93]
	v_pk_fma_f32 v[10:11], v[10:11], v[230:231], v[94:95]
	ds_read_b128 v[228:231], v40 offset:6144
	s_waitcnt lgkmcnt(5)
	v_pk_mul_f32 v[88:89], v[12:13], v[224:225]
	v_pk_fma_f32 v[88:89], v[10:11], v[226:227], v[88:89]
	v_add_f32_e32 v90, v88, v89
	v_pk_mul_f32 v[92:93], v[110:111], v[240:241] op_sel:[1,0] op_sel_hi:[1,1]
	v_pk_mul_f32 v[94:95], v[110:111], v[242:243] op_sel:[1,0] op_sel_hi:[1,1]
	v_add_f32_dpp v90, v90, v90 row_ror:8 row_mask:0xf bank_mask:0xf bound_ctrl:1
	ds_read_b128 v[224:227], v40 offset:18688
	ds_read_b128 v[240:243], v40 offset:10496
	v_add_f32_dpp v90, v90, v90 row_ror:4 row_mask:0xf bank_mask:0xf bound_ctrl:1
	v_pk_mul_f32 v[100:101], v[12:13], v[100:101]
	v_pk_fma_f32 v[100:101], v[10:11], v[102:103], v[100:101]
	v_add_f32_dpp v90, v90, v90 row_ror:2 row_mask:0xf bank_mask:0xf bound_ctrl:1
	v_add_f32_e32 v218, v100, v101
	ds_read_b128 v[100:103], v40 offset:2048
	v_add_f32_dpp v90, v90, v90 row_ror:1 row_mask:0xf bank_mask:0xf bound_ctrl:1
	ds_read2st64_b32 v[110:111], v39 offset0:10 offset1:11
	v_pk_fma_f32 v[92:93], v[90:91], v[248:249], v[92:93] op_sel_hi:[0,1,1]
	v_pk_fma_f32 v[94:95], v[90:91], v[250:251], v[94:95] op_sel_hi:[0,1,1]
	ds_read_b128 v[248:251], v40 offset:22784
	v_pk_fma_f32 v[12:13], v[12:13], v[232:233], v[92:93]
	v_pk_fma_f32 v[10:11], v[10:11], v[234:235], v[94:95]
	ds_read_b128 v[232:235], v40 offset:6400
	s_waitcnt lgkmcnt(6)
	v_pk_mul_f32 v[88:89], v[12:13], v[220:221]
	v_pk_fma_f32 v[88:89], v[10:11], v[222:223], v[88:89]
	v_add_f32_e32 v90, v88, v89
	v_pk_mul_f32 v[92:93], v[108:109], v[236:237] op_sel_hi:[0,1]
	v_pk_mul_f32 v[94:95], v[108:109], v[238:239] op_sel_hi:[0,1]
	v_add_f32_dpp v90, v90, v90 row_ror:8 row_mask:0xf bank_mask:0xf bound_ctrl:1
	ds_read_b128 v[220:223], v40 offset:18944
	ds_read_b128 v[236:239], v40 offset:10752
	v_add_f32_dpp v90, v90, v90 row_ror:4 row_mask:0xf bank_mask:0xf bound_ctrl:1
	v_pk_mul_f32 v[104:105], v[12:13], v[104:105]
	v_pk_fma_f32 v[104:105], v[10:11], v[106:107], v[104:105]
	v_add_f32_dpp v90, v90, v90 row_ror:2 row_mask:0xf bank_mask:0xf bound_ctrl:1
	v_add_f32_e32 v219, v104, v105
	ds_read_b128 v[104:107], v40 offset:2304
	v_add_f32_dpp v90, v90, v90 row_ror:1 row_mask:0xf bank_mask:0xf bound_ctrl:1
	v_pk_fma_f32 v[92:93], v[90:91], v[244:245], v[92:93] op_sel_hi:[0,1,1]
	v_pk_fma_f32 v[94:95], v[90:91], v[246:247], v[94:95] op_sel_hi:[0,1,1]
	ds_read_b128 v[244:247], v40 offset:23040
	v_pk_fma_f32 v[12:13], v[12:13], v[228:229], v[92:93]
	v_pk_fma_f32 v[10:11], v[10:11], v[230:231], v[94:95]
	ds_read_b128 v[228:231], v40 offset:6656
	s_waitcnt lgkmcnt(5)
	v_pk_mul_f32 v[88:89], v[12:13], v[224:225]
	v_pk_fma_f32 v[88:89], v[10:11], v[226:227], v[88:89]
	v_add_f32_e32 v90, v88, v89
	v_pk_mul_f32 v[92:93], v[108:109], v[240:241] op_sel:[1,0] op_sel_hi:[1,1]
	v_pk_mul_f32 v[94:95], v[108:109], v[242:243] op_sel:[1,0] op_sel_hi:[1,1]
	v_add_f32_dpp v90, v90, v90 row_ror:8 row_mask:0xf bank_mask:0xf bound_ctrl:1
	ds_read_b128 v[224:227], v40 offset:19200
	ds_read_b128 v[240:243], v40 offset:11008
	v_add_f32_dpp v90, v90, v90 row_ror:4 row_mask:0xf bank_mask:0xf bound_ctrl:1
	v_pk_mul_f32 v[100:101], v[12:13], v[100:101]
	v_pk_fma_f32 v[100:101], v[10:11], v[102:103], v[100:101]
	v_add_f32_dpp v90, v90, v90 row_ror:2 row_mask:0xf bank_mask:0xf bound_ctrl:1
	v_add_f32_e32 v187, v100, v101
	ds_read_b128 v[100:103], v40 offset:2560
	v_add_f32_dpp v90, v90, v90 row_ror:1 row_mask:0xf bank_mask:0xf bound_ctrl:1
	ds_read2st64_b32 v[108:109], v39 offset0:12 offset1:13
	v_pk_fma_f32 v[92:93], v[90:91], v[248:249], v[92:93] op_sel_hi:[0,1,1]
	v_pk_fma_f32 v[94:95], v[90:91], v[250:251], v[94:95] op_sel_hi:[0,1,1]
	ds_read_b128 v[248:251], v40 offset:23296
	v_pk_fma_f32 v[12:13], v[12:13], v[232:233], v[92:93]
	v_pk_fma_f32 v[10:11], v[10:11], v[234:235], v[94:95]
	ds_read_b128 v[232:235], v40 offset:6912
	s_waitcnt lgkmcnt(6)
	v_pk_mul_f32 v[88:89], v[12:13], v[220:221]
	v_pk_fma_f32 v[88:89], v[10:11], v[222:223], v[88:89]
	v_add_f32_e32 v90, v88, v89
	v_pk_mul_f32 v[92:93], v[110:111], v[236:237] op_sel_hi:[0,1]
	v_pk_mul_f32 v[94:95], v[110:111], v[238:239] op_sel_hi:[0,1]
	v_add_f32_dpp v90, v90, v90 row_ror:8 row_mask:0xf bank_mask:0xf bound_ctrl:1
	ds_read_b128 v[220:223], v40 offset:19456
	ds_read_b128 v[236:239], v40 offset:11264
	v_add_f32_dpp v90, v90, v90 row_ror:4 row_mask:0xf bank_mask:0xf bound_ctrl:1
	v_pk_mul_f32 v[104:105], v[12:13], v[104:105]
	v_pk_fma_f32 v[104:105], v[10:11], v[106:107], v[104:105]
	v_add_f32_dpp v90, v90, v90 row_ror:2 row_mask:0xf bank_mask:0xf bound_ctrl:1
	v_add_f32_e32 v190, v104, v105
	ds_read_b128 v[104:107], v40 offset:2816
	v_add_f32_dpp v90, v90, v90 row_ror:1 row_mask:0xf bank_mask:0xf bound_ctrl:1
	v_pk_fma_f32 v[92:93], v[90:91], v[244:245], v[92:93] op_sel_hi:[0,1,1]
	v_pk_fma_f32 v[94:95], v[90:91], v[246:247], v[94:95] op_sel_hi:[0,1,1]
	ds_read_b128 v[244:247], v40 offset:23552
	v_pk_fma_f32 v[12:13], v[12:13], v[228:229], v[92:93]
	v_pk_fma_f32 v[10:11], v[10:11], v[230:231], v[94:95]
	ds_read_b128 v[228:231], v40 offset:7168
	s_waitcnt lgkmcnt(5)
	v_pk_mul_f32 v[88:89], v[12:13], v[224:225]
	v_pk_fma_f32 v[88:89], v[10:11], v[226:227], v[88:89]
	v_add_f32_e32 v90, v88, v89
	v_pk_mul_f32 v[92:93], v[110:111], v[240:241] op_sel:[1,0] op_sel_hi:[1,1]
	v_pk_mul_f32 v[94:95], v[110:111], v[242:243] op_sel:[1,0] op_sel_hi:[1,1]
	v_add_f32_dpp v90, v90, v90 row_ror:8 row_mask:0xf bank_mask:0xf bound_ctrl:1
	ds_read_b128 v[224:227], v40 offset:19712
	ds_read_b128 v[240:243], v40 offset:11520
	v_add_f32_dpp v90, v90, v90 row_ror:4 row_mask:0xf bank_mask:0xf bound_ctrl:1
	v_pk_mul_f32 v[100:101], v[12:13], v[100:101]
	v_pk_fma_f32 v[100:101], v[10:11], v[102:103], v[100:101]
	v_add_f32_dpp v90, v90, v90 row_ror:2 row_mask:0xf bank_mask:0xf bound_ctrl:1
	v_add_f32_e32 v191, v100, v101
	ds_read_b128 v[100:103], v40 offset:3072
	v_add_f32_dpp v90, v90, v90 row_ror:1 row_mask:0xf bank_mask:0xf bound_ctrl:1
	ds_read2st64_b32 v[110:111], v39 offset0:14 offset1:15
	v_pk_fma_f32 v[92:93], v[90:91], v[248:249], v[92:93] op_sel_hi:[0,1,1]
	v_pk_fma_f32 v[94:95], v[90:91], v[250:251], v[94:95] op_sel_hi:[0,1,1]
	ds_read_b128 v[248:251], v40 offset:23808
	v_pk_fma_f32 v[12:13], v[12:13], v[232:233], v[92:93]
	v_pk_fma_f32 v[10:11], v[10:11], v[234:235], v[94:95]
	ds_read_b128 v[232:235], v40 offset:7424
	s_waitcnt lgkmcnt(6)
	v_pk_mul_f32 v[88:89], v[12:13], v[220:221]
	v_pk_fma_f32 v[88:89], v[10:11], v[222:223], v[88:89]
	v_add_f32_e32 v90, v88, v89
	v_pk_mul_f32 v[92:93], v[108:109], v[236:237] op_sel_hi:[0,1]
	v_pk_mul_f32 v[94:95], v[108:109], v[238:239] op_sel_hi:[0,1]
	v_add_f32_dpp v90, v90, v90 row_ror:8 row_mask:0xf bank_mask:0xf bound_ctrl:1
	ds_read_b128 v[220:223], v40 offset:19968
	ds_read_b128 v[236:239], v40 offset:11776
	v_add_f32_dpp v90, v90, v90 row_ror:4 row_mask:0xf bank_mask:0xf bound_ctrl:1
	v_pk_mul_f32 v[104:105], v[12:13], v[104:105]
	v_pk_fma_f32 v[104:105], v[10:11], v[106:107], v[104:105]
	v_add_f32_dpp v90, v90, v90 row_ror:2 row_mask:0xf bank_mask:0xf bound_ctrl:1
	v_add_f32_e32 v200, v104, v105
	ds_read_b128 v[104:107], v40 offset:3328
	v_add_f32_dpp v90, v90, v90 row_ror:1 row_mask:0xf bank_mask:0xf bound_ctrl:1
	v_pk_fma_f32 v[92:93], v[90:91], v[244:245], v[92:93] op_sel_hi:[0,1,1]
	v_pk_fma_f32 v[94:95], v[90:91], v[246:247], v[94:95] op_sel_hi:[0,1,1]
	ds_read_b128 v[244:247], v40 offset:24064
	v_pk_fma_f32 v[12:13], v[12:13], v[228:229], v[92:93]
	v_pk_fma_f32 v[10:11], v[10:11], v[230:231], v[94:95]
	ds_read_b128 v[228:231], v40 offset:7680
	s_waitcnt lgkmcnt(5)
	v_pk_mul_f32 v[88:89], v[12:13], v[224:225]
	v_pk_fma_f32 v[88:89], v[10:11], v[226:227], v[88:89]
	v_add_f32_e32 v90, v88, v89
	v_pk_mul_f32 v[92:93], v[108:109], v[240:241] op_sel:[1,0] op_sel_hi:[1,1]
	v_pk_mul_f32 v[94:95], v[108:109], v[242:243] op_sel:[1,0] op_sel_hi:[1,1]
	v_add_f32_dpp v90, v90, v90 row_ror:8 row_mask:0xf bank_mask:0xf bound_ctrl:1
	ds_read_b128 v[224:227], v40 offset:20224
	ds_read_b128 v[240:243], v40 offset:12032
	v_add_f32_dpp v90, v90, v90 row_ror:4 row_mask:0xf bank_mask:0xf bound_ctrl:1
	v_pk_mul_f32 v[100:101], v[12:13], v[100:101]
	v_pk_fma_f32 v[100:101], v[10:11], v[102:103], v[100:101]
	v_add_f32_dpp v90, v90, v90 row_ror:2 row_mask:0xf bank_mask:0xf bound_ctrl:1
	v_add_f32_e32 v0, v100, v101
	ds_read_b128 v[100:103], v40 offset:3584
	v_add_f32_dpp v90, v90, v90 row_ror:1 row_mask:0xf bank_mask:0xf bound_ctrl:1
	v_pk_fma_f32 v[92:93], v[90:91], v[248:249], v[92:93] op_sel_hi:[0,1,1]
	v_pk_fma_f32 v[94:95], v[90:91], v[250:251], v[94:95] op_sel_hi:[0,1,1]
	ds_read_b128 v[248:251], v40 offset:24320
	v_pk_fma_f32 v[12:13], v[12:13], v[232:233], v[92:93]
	v_pk_fma_f32 v[10:11], v[10:11], v[234:235], v[94:95]
	ds_read_b128 v[232:235], v40 offset:7936
	s_waitcnt lgkmcnt(5)
	v_pk_mul_f32 v[88:89], v[12:13], v[220:221]
	v_pk_fma_f32 v[88:89], v[10:11], v[222:223], v[88:89]
	v_add_f32_e32 v90, v88, v89
	v_pk_mul_f32 v[92:93], v[110:111], v[236:237] op_sel_hi:[0,1]
	v_pk_mul_f32 v[94:95], v[110:111], v[238:239] op_sel_hi:[0,1]
	v_add_f32_dpp v90, v90, v90 row_ror:8 row_mask:0xf bank_mask:0xf bound_ctrl:1
	s_nop 1
	v_add_f32_dpp v90, v90, v90 row_ror:4 row_mask:0xf bank_mask:0xf bound_ctrl:1
	v_pk_mul_f32 v[104:105], v[12:13], v[104:105]
	v_pk_fma_f32 v[104:105], v[10:11], v[106:107], v[104:105]
	v_add_f32_dpp v90, v90, v90 row_ror:2 row_mask:0xf bank_mask:0xf bound_ctrl:1
	v_add_f32_e32 v84, v104, v105
	ds_read_b128 v[104:107], v40 offset:3840
	v_add_f32_dpp v90, v90, v90 row_ror:1 row_mask:0xf bank_mask:0xf bound_ctrl:1
	v_pk_fma_f32 v[92:93], v[90:91], v[244:245], v[92:93] op_sel_hi:[0,1,1]
	v_pk_fma_f32 v[94:95], v[90:91], v[246:247], v[94:95] op_sel_hi:[0,1,1]
	v_pk_fma_f32 v[12:13], v[12:13], v[228:229], v[92:93]
	v_pk_fma_f32 v[10:11], v[10:11], v[230:231], v[94:95]
	s_waitcnt lgkmcnt(1)
	v_pk_mul_f32 v[88:89], v[12:13], v[224:225]
	v_pk_fma_f32 v[88:89], v[10:11], v[226:227], v[88:89]
	v_add_f32_e32 v90, v88, v89
	v_pk_mul_f32 v[92:93], v[110:111], v[240:241] op_sel:[1,0] op_sel_hi:[1,1]
	v_pk_mul_f32 v[94:95], v[110:111], v[242:243] op_sel:[1,0] op_sel_hi:[1,1]
	v_add_f32_dpp v90, v90, v90 row_ror:8 row_mask:0xf bank_mask:0xf bound_ctrl:1
	s_nop 1
	v_add_f32_dpp v90, v90, v90 row_ror:4 row_mask:0xf bank_mask:0xf bound_ctrl:1
	v_pk_mul_f32 v[100:101], v[12:13], v[100:101]
	v_pk_fma_f32 v[100:101], v[10:11], v[102:103], v[100:101]
	v_add_f32_dpp v90, v90, v90 row_ror:2 row_mask:0xf bank_mask:0xf bound_ctrl:1
	v_add_f32_e32 v85, v100, v101
	s_nop 0
	v_add_f32_dpp v90, v90, v90 row_ror:1 row_mask:0xf bank_mask:0xf bound_ctrl:1
	v_pk_fma_f32 v[92:93], v[90:91], v[248:249], v[92:93] op_sel_hi:[0,1,1]
	v_pk_fma_f32 v[94:95], v[90:91], v[250:251], v[94:95] op_sel_hi:[0,1,1]
	v_pk_fma_f32 v[12:13], v[12:13], v[232:233], v[92:93]
	v_pk_fma_f32 v[10:11], v[10:11], v[234:235], v[94:95]
	s_waitcnt lgkmcnt(0)
	v_pk_mul_f32 v[104:105], v[12:13], v[104:105]
	v_pk_fma_f32 v[104:105], v[10:11], v[106:107], v[104:105]
	v_add_f32_dpp v96, v96, v96 row_mirror row_mask:0xf bank_mask:0x3
	v_add_f32_dpp v96, v187, v187 row_mirror row_mask:0xf bank_mask:0xc
	v_add_f32_e32 v86, v104, v105
	v_add_f32_dpp v97, v97, v97 row_mirror row_mask:0xf bank_mask:0x3
	v_add_f32_dpp v97, v190, v190 row_mirror row_mask:0xf bank_mask:0xc
	v_add_f32_dpp v98, v98, v98 row_mirror row_mask:0xf bank_mask:0x3
	v_add_f32_dpp v98, v191, v191 row_mirror row_mask:0xf bank_mask:0xc
	v_add_f32_dpp v99, v99, v99 row_mirror row_mask:0xf bank_mask:0x3
	v_add_f32_dpp v99, v200, v200 row_mirror row_mask:0xf bank_mask:0xc
	v_add_f32_dpp v87, v87, v87 row_mirror row_mask:0xf bank_mask:0x3
	v_add_f32_dpp v87, v0, v0 row_mirror row_mask:0xf bank_mask:0xc
	v_add_f32_dpp v217, v217, v217 row_mirror row_mask:0xf bank_mask:0x3
	v_add_f32_dpp v217, v84, v84 row_mirror row_mask:0xf bank_mask:0xc
	v_add_f32_dpp v218, v218, v218 row_mirror row_mask:0xf bank_mask:0x3
	v_add_f32_dpp v218, v85, v85 row_mirror row_mask:0xf bank_mask:0xc
	v_add_f32_dpp v219, v219, v219 row_mirror row_mask:0xf bank_mask:0x3
	v_add_f32_dpp v219, v86, v86 row_mirror row_mask:0xf bank_mask:0xc
	v_add_f32_dpp v96, v96, v96 row_half_mirror row_mask:0xf bank_mask:0x5
	v_add_f32_dpp v96, v87, v87 row_half_mirror row_mask:0xf bank_mask:0xa
	v_add_f32_dpp v97, v97, v97 row_half_mirror row_mask:0xf bank_mask:0x5
	v_add_f32_dpp v97, v217, v217 row_half_mirror row_mask:0xf bank_mask:0xa
	v_add_f32_dpp v98, v98, v98 row_half_mirror row_mask:0xf bank_mask:0x5
	v_add_f32_dpp v98, v218, v218 row_half_mirror row_mask:0xf bank_mask:0xa
	v_add_f32_dpp v99, v99, v99 row_half_mirror row_mask:0xf bank_mask:0x5
	v_add_f32_dpp v99, v219, v219 row_half_mirror row_mask:0xf bank_mask:0xa
	s_mov_b32 vcc_lo, 0xcccccccc
	s_mov_b32 vcc_hi, 0xcccccccc
	v_cndmask_b32_e32 v187, v96, v98, vcc
	v_cndmask_b32_e32 v190, v98, v96, vcc
	v_cndmask_b32_e32 v200, v99, v97, vcc
	v_cndmask_b32_e32 v191, v97, v99, vcc
	v_add_f32_dpp v0, v190, v187 quad_perm:[2,3,0,1] row_mask:0xf bank_mask:0xf bound_ctrl:1
	v_add_f32_dpp v84, v200, v191 quad_perm:[2,3,0,1] row_mask:0xf bank_mask:0xf bound_ctrl:1
	s_mov_b32 vcc_lo, 0xaaaaaaaa
	s_mov_b32 vcc_hi, 0xaaaaaaaa
	v_cndmask_b32_e32 v85, v0, v84, vcc
	v_cndmask_b32_e32 v86, v84, v0, vcc
	s_nop 1
	v_add_f32_dpp v86, v86, v85 quad_perm:[1,0,3,2] row_mask:0xf bank_mask:0xf bound_ctrl:1
	v_lshl_or_b32 v84, s4, 4, v31
	v_or_b32_e32 v84, s56, v84
	v_mov_b32_e32 v85, s57
	s_waitcnt vmcnt(38)
	v_lshlrev_b32_e32 v15, 16, v15
	v_lshlrev_b64 v[84:85], 10, v[84:85]
	v_mul_f32_e32 v15, 0x3fb8aa3b, v15
	v_cvt_pk_bf16_f32 v0, v86, s0
	v_lshl_add_u64 v[84:85], v[6:7], 0, v[84:85]
	v_lshlrev_b32_e32 v75, 16, v75
	v_lshlrev_b32_e32 v78, 16, v78
	v_exp_f32_e32 v15, v15
	s_waitcnt vmcnt(37)
	v_lshlrev_b32_e32 v43, 16, v43
	global_store_short v[84:85], v0, off
	v_sub_f32_e32 v78, v78, v75
	v_add_f32_e32 v84, -1.0, v43
	v_lshlrev_b32_e32 v81, 16, v81
	v_lshlrev_b32_e32 v79, 16, v79
	v_fma_f32 v78, v16, v78, v75
	v_fma_f32 v84, v19, v84, 1.0
	v_lshlrev_b32_e32 v0, 16, v82
	v_sub_f32_e32 v79, v79, v81
	v_mul_f32_e32 v82, v18, v78
	v_mul_f32_e32 v78, v78, v84
	v_fma_f32 v79, v17, v79, v81
	ds_write2st64_b32 v32, v15, v78 offset0:112 offset1:128
	s_waitcnt vmcnt(37)
	v_mul_f32_e64 v15, v82, -v44
	s_waitcnt vmcnt(36)
	v_lshlrev_b32_e32 v48, 16, v48
	v_lshlrev_b32_e32 v80, 16, v80
	ds_write2st64_b32 v32, v79, v15 offset0:144 offset1:160
	v_mul_f32_e64 v15, -v15, v43
	v_lshlrev_b32_e32 v43, 16, v74
	v_mul_f32_e32 v48, 0x3fb8aa3b, v48
	v_sub_f32_e32 v80, v80, v0
	ds_write_b32 v32, v15 offset:45056
	v_lshlrev_b32_e32 v15, 16, v76
	v_sub_f32_e32 v74, v75, v43
	v_exp_f32_e32 v48, v48
	s_waitcnt vmcnt(35)
	v_lshlrev_b32_e32 v49, 16, v49
	v_fma_f32 v80, v3, v80, v0
	v_lshlrev_b32_e32 v44, 16, v77
	v_sub_f32_e32 v0, v0, v15
	v_fma_f32 v74, v16, v74, v43
	v_add_f32_e32 v77, -1.0, v49
	v_fma_f32 v0, v3, v0, v15
	v_sub_f32_e32 v75, v81, v44
	v_mul_f32_e32 v76, v18, v74
	v_fma_f32 v77, v19, v77, 1.0
	v_fma_f32 v75, v17, v75, v44
	v_mul_f32_e32 v74, v74, v77
	ds_write2st64_b32 v32, v80, v0 offset0:96 offset1:97
	ds_write_b32 v33, v48 offset:24832
	ds_write_b32 v34, v74 offset:24832
	ds_write_b32 v35, v75 offset:24832
	s_waitcnt vmcnt(34)
	v_mul_f32_e64 v0, v76, -v46
	s_waitcnt vmcnt(33)
	v_lshlrev_b32_e32 v45, 16, v45
	ds_write_b32 v36, v0 offset:24832
	v_mul_f32_e64 v0, -v0, v49
	v_lshlrev_b32_e32 v46, 16, v69
	v_mul_f32_e32 v45, 0x3fb8aa3b, v45
	ds_write_b32 v37, v0 offset:24832
	v_lshlrev_b32_e32 v0, 16, v72
	v_sub_f32_e32 v43, v43, v46
	v_exp_f32_e32 v45, v45
	s_waitcnt vmcnt(32)
	v_lshlrev_b32_e32 v47, 16, v47
	v_lshlrev_b32_e32 v48, 16, v73
	v_sub_f32_e32 v15, v15, v0
	v_fma_f32 v43, v16, v43, v46
	v_add_f32_e32 v69, -1.0, v47
	v_fma_f32 v15, v3, v15, v0
	v_sub_f32_e32 v44, v44, v48
	v_mul_f32_e32 v49, v18, v43
	v_fma_f32 v69, v19, v69, 1.0
	v_fma_f32 v44, v17, v44, v48
	v_mul_f32_e32 v43, v43, v69
	ds_write_b32 v32, v15 offset:25088
	ds_write_b32 v33, v45 offset:25088
	ds_write_b32 v34, v43 offset:25088
	ds_write_b32 v35, v44 offset:25088
	s_waitcnt vmcnt(31)
	v_mul_f32_e64 v15, v49, -v52
	ds_write_b32 v36, v15 offset:25088
	v_mul_f32_e64 v15, -v15, v47
	ds_write_b32 v37, v15 offset:25088
	v_lshlrev_b32_e32 v15, 16, v70
	v_lshlrev_b32_e32 v14, 16, v14
	v_sub_f32_e32 v0, v0, v15
	v_lshlrev_b32_e32 v43, 16, v71
	v_fmac_f32_e32 v15, v3, v0
	v_sub_f32_e32 v0, v46, v14
	v_fmac_f32_e32 v14, v16, v0
	v_sub_f32_e32 v0, v48, v43
	v_fmac_f32_e32 v43, v17, v0
	s_waitcnt vmcnt(30)
	v_lshlrev_b32_e32 v0, 16, v50
	v_mul_f32_e32 v0, 0x3fb8aa3b, v0
	v_exp_f32_e32 v0, v0
	s_waitcnt vmcnt(29)
	v_lshlrev_b32_e32 v44, 16, v51
	v_add_f32_e32 v46, -1.0, v44
	s_or_b32 s5, s4, 1
	v_mul_f32_e32 v45, v18, v14
	v_fma_f32 v46, v19, v46, 1.0
	v_mul_f32_e32 v14, v14, v46
	ds_write_b32 v32, v15 offset:25344
	ds_write_b32 v33, v0 offset:25344
	ds_write_b32 v34, v14 offset:25344
	ds_write_b32 v35, v43 offset:25344
	s_waitcnt vmcnt(28)
	v_mul_f32_e64 v0, v45, -v53
	s_min_u32 s6, s5, 0xfd
	ds_write_b32 v36, v0 offset:25344
	v_mul_f32_e64 v0, -v0, v44
	v_lshl_add_u32 v14, s6, 4, v38
	ds_write_b32 v37, v0 offset:25344
	v_max_i32_e32 v0, 1, v14
	v_add_u32_e32 v0, -1, v0
	v_lshl_add_u64 v[44:45], s[56:57], 0, v[0:1]
	v_mad_u64_u32 v[46:47], s[6:7], v44, s29, v[4:5]
	v_max_i32_e32 v0, 0, v14
	v_mad_i32_i24 v47, v45, s29, v47
	v_lshl_add_u64 v[44:45], s[56:57], 0, v[0:1]
	v_max_i32_e32 v0, -1, v14
	s_waitcnt lgkmcnt(0)
	s_barrier
	ds_read_b128 v[220:223], v42 offset:16384
	ds_read_b128 v[236:239], v42 offset:8192
	ds_read2st64_b32 v[108:109], v41 offset0:0 offset1:1
	ds_read_b128 v[244:247], v42 offset:20480
	ds_read_b128 v[228:231], v42 offset:4096
	ds_read_b128 v[100:103], v42 offset:0
	ds_read_b128 v[224:227], v42 offset:16640
	ds_read_b128 v[240:243], v42 offset:8448
	ds_read2st64_b32 v[110:111], v41 offset0:2 offset1:3
	ds_read_b128 v[248:251], v42 offset:20736
	ds_read_b128 v[232:235], v42 offset:4352
	s_mov_b64 s[6:7], 0xd00
	global_load_ushort v70, v[46:47], off
	global_load_ushort v72, v[46:47], off offset:1024
	global_load_ushort v71, v[46:47], off offset:2048
	v_lshl_add_u64 v[112:113], v[46:47], 0, s[6:7]
	v_lshl_add_u64 v[114:115], v[112:113], 0, s[6:7]
	v_lshl_add_u64 v[116:117], v[114:115], 0, s[6:7]
	v_lshl_add_u64 v[118:119], v[116:117], 0, s[6:7]
	v_ashrrev_i32_e32 v15, 31, v14
	v_lshl_add_u64 v[120:121], s[56:57], 0, v[14:15]
	v_lshlrev_b64 v[122:123], 10, v[120:121]
	v_or_b32_e32 v122, v122, v83
	v_lshl_add_u64 v[124:125], s[0:1], 0, v[122:123]
	v_lshl_add_u64 v[126:127], s[24:25], 0, v[122:123]
	v_lshlrev_b64 v[128:129], 5, v[120:121]
	v_lshl_add_u64 v[128:129], s[58:59], 0, v[128:129]
	global_load_ushort v73, v[112:113], off
	global_load_ushort v69, v[112:113], off offset:1024
	global_load_ushort v76, v[112:113], off offset:2048
	global_load_ushort v77, v[114:115], off
	global_load_ushort v74, v[114:115], off offset:1024
	global_load_ushort v84, v[114:115], off offset:2048
	global_load_ushort v78, v[116:117], off offset:1024
	global_load_ushort v85, v[116:117], off offset:2048
	global_load_ushort v15, v[124:125], off
	global_load_ushort v43, v[126:127], off
	global_load_dword v44, v[128:129], off
	global_load_ushort v48, v[124:125], off offset:1024
	global_load_ushort v49, v[126:127], off offset:1024
	global_load_dword v46, v[128:129], off offset:32
	global_load_ushort v45, v[124:125], off offset:2048
	global_load_ushort v47, v[126:127], off offset:2048
	global_load_ushort v83, v[116:117], off
	global_load_ushort v0, v[118:119], off
	global_load_ushort v79, v[118:119], off offset:1024
	global_load_ushort v86, v[118:119], off offset:2048
	global_load_dword v52, v[128:129], off offset:64
	global_load_ushort v50, v[124:125], off offset:3072
	global_load_ushort v51, v[126:127], off offset:3072
	global_load_dword v53, v[128:129], off offset:96
	s_mov_b32 s6, 0
	v_mov_b32_e32 v87, 0
	v_mov_b32_e32 v75, v31
	v_mov_b32_e32 v80, v42
	v_mov_b32_e32 v81, v41
	s_waitcnt lgkmcnt(6)
	v_pk_mul_f32 v[88:89], v[12:13], v[220:221]
	v_pk_fma_f32 v[88:89], v[10:11], v[222:223], v[88:89]
	v_add_f32_e32 v90, v88, v89
	v_pk_mul_f32 v[92:93], v[108:109], v[236:237] op_sel_hi:[0,1]
	v_pk_mul_f32 v[94:95], v[108:109], v[238:239] op_sel_hi:[0,1]
	v_add_f32_dpp v90, v90, v90 row_ror:8 row_mask:0xf bank_mask:0xf bound_ctrl:1
	ds_read_b128 v[220:223], v42 offset:16896
	ds_read_b128 v[236:239], v42 offset:8704
	v_add_f32_dpp v90, v90, v90 row_ror:4 row_mask:0xf bank_mask:0xf bound_ctrl:1
	s_nop 1
	v_add_f32_dpp v90, v90, v90 row_ror:2 row_mask:0xf bank_mask:0xf bound_ctrl:1
	ds_read_b128 v[104:107], v42 offset:256
	s_nop 0
	v_add_f32_dpp v90, v90, v90 row_ror:1 row_mask:0xf bank_mask:0xf bound_ctrl:1
	v_pk_fma_f32 v[92:93], v[90:91], v[244:245], v[92:93] op_sel_hi:[0,1,1]
	v_pk_fma_f32 v[94:95], v[90:91], v[246:247], v[94:95] op_sel_hi:[0,1,1]
	ds_read_b128 v[244:247], v42 offset:20992
	v_pk_fma_f32 v[12:13], v[12:13], v[228:229], v[92:93]
	v_pk_fma_f32 v[10:11], v[10:11], v[230:231], v[94:95]
	ds_read_b128 v[228:231], v42 offset:4608
	s_waitcnt lgkmcnt(5)
	v_pk_mul_f32 v[88:89], v[12:13], v[224:225]
	v_pk_fma_f32 v[88:89], v[10:11], v[226:227], v[88:89]
	v_add_f32_e32 v90, v88, v89
	v_pk_mul_f32 v[92:93], v[108:109], v[240:241] op_sel:[1,0] op_sel_hi:[1,1]
	v_pk_mul_f32 v[94:95], v[108:109], v[242:243] op_sel:[1,0] op_sel_hi:[1,1]
	v_add_f32_dpp v90, v90, v90 row_ror:8 row_mask:0xf bank_mask:0xf bound_ctrl:1
	ds_read_b128 v[224:227], v42 offset:17152
	ds_read_b128 v[240:243], v42 offset:8960
	v_add_f32_dpp v90, v90, v90 row_ror:4 row_mask:0xf bank_mask:0xf bound_ctrl:1
	v_pk_mul_f32 v[100:101], v[12:13], v[100:101]
	v_pk_fma_f32 v[100:101], v[10:11], v[102:103], v[100:101]
	v_add_f32_dpp v90, v90, v90 row_ror:2 row_mask:0xf bank_mask:0xf bound_ctrl:1
	v_add_f32_e32 v96, v100, v101
	ds_read_b128 v[100:103], v42 offset:512
	v_add_f32_dpp v90, v90, v90 row_ror:1 row_mask:0xf bank_mask:0xf bound_ctrl:1
	ds_read2st64_b32 v[108:109], v41 offset0:4 offset1:5
	v_pk_fma_f32 v[92:93], v[90:91], v[248:249], v[92:93] op_sel_hi:[0,1,1]
	v_pk_fma_f32 v[94:95], v[90:91], v[250:251], v[94:95] op_sel_hi:[0,1,1]
	ds_read_b128 v[248:251], v42 offset:21248
	v_pk_fma_f32 v[12:13], v[12:13], v[232:233], v[92:93]
	v_pk_fma_f32 v[10:11], v[10:11], v[234:235], v[94:95]
	ds_read_b128 v[232:235], v42 offset:4864
	s_waitcnt lgkmcnt(6)
	v_pk_mul_f32 v[88:89], v[12:13], v[220:221]
	v_pk_fma_f32 v[88:89], v[10:11], v[222:223], v[88:89]
	v_add_f32_e32 v90, v88, v89
	v_pk_mul_f32 v[92:93], v[110:111], v[236:237] op_sel_hi:[0,1]
	v_pk_mul_f32 v[94:95], v[110:111], v[238:239] op_sel_hi:[0,1]
	v_add_f32_dpp v90, v90, v90 row_ror:8 row_mask:0xf bank_mask:0xf bound_ctrl:1
	ds_read_b128 v[220:223], v42 offset:17408
	ds_read_b128 v[236:239], v42 offset:9216
	v_add_f32_dpp v90, v90, v90 row_ror:4 row_mask:0xf bank_mask:0xf bound_ctrl:1
	v_pk_mul_f32 v[104:105], v[12:13], v[104:105]
	v_pk_fma_f32 v[104:105], v[10:11], v[106:107], v[104:105]
	v_add_f32_dpp v90, v90, v90 row_ror:2 row_mask:0xf bank_mask:0xf bound_ctrl:1
	v_add_f32_e32 v97, v104, v105
	ds_read_b128 v[104:107], v42 offset:768
	v_add_f32_dpp v90, v90, v90 row_ror:1 row_mask:0xf bank_mask:0xf bound_ctrl:1
	v_pk_fma_f32 v[92:93], v[90:91], v[244:245], v[92:93] op_sel_hi:[0,1,1]
	v_pk_fma_f32 v[94:95], v[90:91], v[246:247], v[94:95] op_sel_hi:[0,1,1]
	ds_read_b128 v[244:247], v42 offset:21504
	v_pk_fma_f32 v[12:13], v[12:13], v[228:229], v[92:93]
	v_pk_fma_f32 v[10:11], v[10:11], v[230:231], v[94:95]
	ds_read_b128 v[228:231], v42 offset:5120
	s_waitcnt lgkmcnt(5)
	v_pk_mul_f32 v[88:89], v[12:13], v[224:225]
	v_pk_fma_f32 v[88:89], v[10:11], v[226:227], v[88:89]
	v_add_f32_e32 v90, v88, v89
	v_pk_mul_f32 v[92:93], v[110:111], v[240:241] op_sel:[1,0] op_sel_hi:[1,1]
	v_pk_mul_f32 v[94:95], v[110:111], v[242:243] op_sel:[1,0] op_sel_hi:[1,1]
	v_add_f32_dpp v90, v90, v90 row_ror:8 row_mask:0xf bank_mask:0xf bound_ctrl:1
	ds_read_b128 v[224:227], v42 offset:17664
	ds_read_b128 v[240:243], v42 offset:9472
	v_add_f32_dpp v90, v90, v90 row_ror:4 row_mask:0xf bank_mask:0xf bound_ctrl:1
	v_pk_mul_f32 v[100:101], v[12:13], v[100:101]
	v_pk_fma_f32 v[100:101], v[10:11], v[102:103], v[100:101]
	v_add_f32_dpp v90, v90, v90 row_ror:2 row_mask:0xf bank_mask:0xf bound_ctrl:1
	v_add_f32_e32 v98, v100, v101
	ds_read_b128 v[100:103], v42 offset:1024
	v_add_f32_dpp v90, v90, v90 row_ror:1 row_mask:0xf bank_mask:0xf bound_ctrl:1
	ds_read2st64_b32 v[110:111], v41 offset0:6 offset1:7
	v_pk_fma_f32 v[92:93], v[90:91], v[248:249], v[92:93] op_sel_hi:[0,1,1]
	v_pk_fma_f32 v[94:95], v[90:91], v[250:251], v[94:95] op_sel_hi:[0,1,1]
	ds_read_b128 v[248:251], v42 offset:21760
	v_pk_fma_f32 v[12:13], v[12:13], v[232:233], v[92:93]
	v_pk_fma_f32 v[10:11], v[10:11], v[234:235], v[94:95]
	ds_read_b128 v[232:235], v42 offset:5376
	s_waitcnt lgkmcnt(6)
	v_pk_mul_f32 v[88:89], v[12:13], v[220:221]
	v_pk_fma_f32 v[88:89], v[10:11], v[222:223], v[88:89]
	v_add_f32_e32 v90, v88, v89
	v_pk_mul_f32 v[92:93], v[108:109], v[236:237] op_sel_hi:[0,1]
	v_pk_mul_f32 v[94:95], v[108:109], v[238:239] op_sel_hi:[0,1]
	v_add_f32_dpp v90, v90, v90 row_ror:8 row_mask:0xf bank_mask:0xf bound_ctrl:1
	ds_read_b128 v[220:223], v42 offset:17920
	ds_read_b128 v[236:239], v42 offset:9728
	v_add_f32_dpp v90, v90, v90 row_ror:4 row_mask:0xf bank_mask:0xf bound_ctrl:1
	v_pk_mul_f32 v[104:105], v[12:13], v[104:105]
	v_pk_fma_f32 v[104:105], v[10:11], v[106:107], v[104:105]
	v_add_f32_dpp v90, v90, v90 row_ror:2 row_mask:0xf bank_mask:0xf bound_ctrl:1
	v_add_f32_e32 v99, v104, v105
	ds_read_b128 v[104:107], v42 offset:1280
	v_add_f32_dpp v90, v90, v90 row_ror:1 row_mask:0xf bank_mask:0xf bound_ctrl:1
	v_pk_fma_f32 v[92:93], v[90:91], v[244:245], v[92:93] op_sel_hi:[0,1,1]
	v_pk_fma_f32 v[94:95], v[90:91], v[246:247], v[94:95] op_sel_hi:[0,1,1]
	ds_read_b128 v[244:247], v42 offset:22016
	v_pk_fma_f32 v[12:13], v[12:13], v[228:229], v[92:93]
	v_pk_fma_f32 v[10:11], v[10:11], v[230:231], v[94:95]
	ds_read_b128 v[228:231], v42 offset:5632
	s_waitcnt lgkmcnt(5)
	v_pk_mul_f32 v[88:89], v[12:13], v[224:225]
	v_pk_fma_f32 v[88:89], v[10:11], v[226:227], v[88:89]
	v_add_f32_e32 v90, v88, v89
	v_pk_mul_f32 v[92:93], v[108:109], v[240:241] op_sel:[1,0] op_sel_hi:[1,1]
	v_pk_mul_f32 v[94:95], v[108:109], v[242:243] op_sel:[1,0] op_sel_hi:[1,1]
	v_add_f32_dpp v90, v90, v90 row_ror:8 row_mask:0xf bank_mask:0xf bound_ctrl:1
	ds_read_b128 v[224:227], v42 offset:18176
	ds_read_b128 v[240:243], v42 offset:9984
	v_add_f32_dpp v90, v90, v90 row_ror:4 row_mask:0xf bank_mask:0xf bound_ctrl:1
	v_pk_mul_f32 v[100:101], v[12:13], v[100:101]
	v_pk_fma_f32 v[100:101], v[10:11], v[102:103], v[100:101]
	v_add_f32_dpp v90, v90, v90 row_ror:2 row_mask:0xf bank_mask:0xf bound_ctrl:1
	v_add_f32_e32 v87, v100, v101
	ds_read_b128 v[100:103], v42 offset:1536
	v_add_f32_dpp v90, v90, v90 row_ror:1 row_mask:0xf bank_mask:0xf bound_ctrl:1
	ds_read2st64_b32 v[108:109], v41 offset0:8 offset1:9
	v_pk_fma_f32 v[92:93], v[90:91], v[248:249], v[92:93] op_sel_hi:[0,1,1]
	v_pk_fma_f32 v[94:95], v[90:91], v[250:251], v[94:95] op_sel_hi:[0,1,1]
	ds_read_b128 v[248:251], v42 offset:22272
	v_pk_fma_f32 v[12:13], v[12:13], v[232:233], v[92:93]
	v_pk_fma_f32 v[10:11], v[10:11], v[234:235], v[94:95]
	ds_read_b128 v[232:235], v42 offset:5888
	s_waitcnt lgkmcnt(6)
	v_pk_mul_f32 v[88:89], v[12:13], v[220:221]
	v_pk_fma_f32 v[88:89], v[10:11], v[222:223], v[88:89]
	v_add_f32_e32 v90, v88, v89
	v_pk_mul_f32 v[92:93], v[110:111], v[236:237] op_sel_hi:[0,1]
	v_pk_mul_f32 v[94:95], v[110:111], v[238:239] op_sel_hi:[0,1]
	v_add_f32_dpp v90, v90, v90 row_ror:8 row_mask:0xf bank_mask:0xf bound_ctrl:1
	ds_read_b128 v[220:223], v42 offset:18432
	ds_read_b128 v[236:239], v42 offset:10240
	v_add_f32_dpp v90, v90, v90 row_ror:4 row_mask:0xf bank_mask:0xf bound_ctrl:1
	v_pk_mul_f32 v[104:105], v[12:13], v[104:105]
	v_pk_fma_f32 v[104:105], v[10:11], v[106:107], v[104:105]
	v_add_f32_dpp v90, v90, v90 row_ror:2 row_mask:0xf bank_mask:0xf bound_ctrl:1
	v_add_f32_e32 v217, v104, v105
	ds_read_b128 v[104:107], v42 offset:1792
	v_add_f32_dpp v90, v90, v90 row_ror:1 row_mask:0xf bank_mask:0xf bound_ctrl:1
	v_pk_fma_f32 v[92:93], v[90:91], v[244:245], v[92:93] op_sel_hi:[0,1,1]
	v_pk_fma_f32 v[94:95], v[90:91], v[246:247], v[94:95] op_sel_hi:[0,1,1]
	ds_read_b128 v[244:247], v42 offset:22528
	v_pk_fma_f32 v[12:13], v[12:13], v[228:229], v[92:93]
	v_pk_fma_f32 v[10:11], v[10:11], v[230:231], v[94:95]
	ds_read_b128 v[228:231], v42 offset:6144
	s_waitcnt lgkmcnt(5)
	v_pk_mul_f32 v[88:89], v[12:13], v[224:225]
	v_pk_fma_f32 v[88:89], v[10:11], v[226:227], v[88:89]
	v_add_f32_e32 v90, v88, v89
	v_pk_mul_f32 v[92:93], v[110:111], v[240:241] op_sel:[1,0] op_sel_hi:[1,1]
	v_pk_mul_f32 v[94:95], v[110:111], v[242:243] op_sel:[1,0] op_sel_hi:[1,1]
	v_add_f32_dpp v90, v90, v90 row_ror:8 row_mask:0xf bank_mask:0xf bound_ctrl:1
	ds_read_b128 v[224:227], v42 offset:18688
	ds_read_b128 v[240:243], v42 offset:10496
	v_add_f32_dpp v90, v90, v90 row_ror:4 row_mask:0xf bank_mask:0xf bound_ctrl:1
	v_pk_mul_f32 v[100:101], v[12:13], v[100:101]
	v_pk_fma_f32 v[100:101], v[10:11], v[102:103], v[100:101]
	v_add_f32_dpp v90, v90, v90 row_ror:2 row_mask:0xf bank_mask:0xf bound_ctrl:1
	v_add_f32_e32 v218, v100, v101
	ds_read_b128 v[100:103], v42 offset:2048
	v_add_f32_dpp v90, v90, v90 row_ror:1 row_mask:0xf bank_mask:0xf bound_ctrl:1
	ds_read2st64_b32 v[110:111], v41 offset0:10 offset1:11
	v_pk_fma_f32 v[92:93], v[90:91], v[248:249], v[92:93] op_sel_hi:[0,1,1]
	v_pk_fma_f32 v[94:95], v[90:91], v[250:251], v[94:95] op_sel_hi:[0,1,1]
	ds_read_b128 v[248:251], v42 offset:22784
	v_pk_fma_f32 v[12:13], v[12:13], v[232:233], v[92:93]
	v_pk_fma_f32 v[10:11], v[10:11], v[234:235], v[94:95]
	ds_read_b128 v[232:235], v42 offset:6400
	s_waitcnt lgkmcnt(6)
	v_pk_mul_f32 v[88:89], v[12:13], v[220:221]
	v_pk_fma_f32 v[88:89], v[10:11], v[222:223], v[88:89]
	v_add_f32_e32 v90, v88, v89
	v_pk_mul_f32 v[92:93], v[108:109], v[236:237] op_sel_hi:[0,1]
	v_pk_mul_f32 v[94:95], v[108:109], v[238:239] op_sel_hi:[0,1]
	v_add_f32_dpp v90, v90, v90 row_ror:8 row_mask:0xf bank_mask:0xf bound_ctrl:1
	ds_read_b128 v[220:223], v42 offset:18944
	ds_read_b128 v[236:239], v42 offset:10752
	v_add_f32_dpp v90, v90, v90 row_ror:4 row_mask:0xf bank_mask:0xf bound_ctrl:1
	v_pk_mul_f32 v[104:105], v[12:13], v[104:105]
	v_pk_fma_f32 v[104:105], v[10:11], v[106:107], v[104:105]
	v_add_f32_dpp v90, v90, v90 row_ror:2 row_mask:0xf bank_mask:0xf bound_ctrl:1
	v_add_f32_e32 v219, v104, v105
	ds_read_b128 v[104:107], v42 offset:2304
	v_add_f32_dpp v90, v90, v90 row_ror:1 row_mask:0xf bank_mask:0xf bound_ctrl:1
	v_pk_fma_f32 v[92:93], v[90:91], v[244:245], v[92:93] op_sel_hi:[0,1,1]
	v_pk_fma_f32 v[94:95], v[90:91], v[246:247], v[94:95] op_sel_hi:[0,1,1]
	ds_read_b128 v[244:247], v42 offset:23040
	v_pk_fma_f32 v[12:13], v[12:13], v[228:229], v[92:93]
	v_pk_fma_f32 v[10:11], v[10:11], v[230:231], v[94:95]
	ds_read_b128 v[228:231], v42 offset:6656
	s_waitcnt lgkmcnt(5)
	v_pk_mul_f32 v[88:89], v[12:13], v[224:225]
	v_pk_fma_f32 v[88:89], v[10:11], v[226:227], v[88:89]
	v_add_f32_e32 v90, v88, v89
	v_pk_mul_f32 v[92:93], v[108:109], v[240:241] op_sel:[1,0] op_sel_hi:[1,1]
	v_pk_mul_f32 v[94:95], v[108:109], v[242:243] op_sel:[1,0] op_sel_hi:[1,1]
	v_add_f32_dpp v90, v90, v90 row_ror:8 row_mask:0xf bank_mask:0xf bound_ctrl:1
	ds_read_b128 v[224:227], v42 offset:19200
	ds_read_b128 v[240:243], v42 offset:11008
	v_add_f32_dpp v90, v90, v90 row_ror:4 row_mask:0xf bank_mask:0xf bound_ctrl:1
	v_pk_mul_f32 v[100:101], v[12:13], v[100:101]
	v_pk_fma_f32 v[100:101], v[10:11], v[102:103], v[100:101]
	v_add_f32_dpp v90, v90, v90 row_ror:2 row_mask:0xf bank_mask:0xf bound_ctrl:1
	v_add_f32_e32 v187, v100, v101
	ds_read_b128 v[100:103], v42 offset:2560
	v_add_f32_dpp v90, v90, v90 row_ror:1 row_mask:0xf bank_mask:0xf bound_ctrl:1
	ds_read2st64_b32 v[108:109], v41 offset0:12 offset1:13
	v_pk_fma_f32 v[92:93], v[90:91], v[248:249], v[92:93] op_sel_hi:[0,1,1]
	v_pk_fma_f32 v[94:95], v[90:91], v[250:251], v[94:95] op_sel_hi:[0,1,1]
	ds_read_b128 v[248:251], v42 offset:23296
	v_pk_fma_f32 v[12:13], v[12:13], v[232:233], v[92:93]
	v_pk_fma_f32 v[10:11], v[10:11], v[234:235], v[94:95]
	ds_read_b128 v[232:235], v42 offset:6912
	s_waitcnt lgkmcnt(6)
	v_pk_mul_f32 v[88:89], v[12:13], v[220:221]
	v_pk_fma_f32 v[88:89], v[10:11], v[222:223], v[88:89]
	v_add_f32_e32 v90, v88, v89
	v_pk_mul_f32 v[92:93], v[110:111], v[236:237] op_sel_hi:[0,1]
	v_pk_mul_f32 v[94:95], v[110:111], v[238:239] op_sel_hi:[0,1]
	v_add_f32_dpp v90, v90, v90 row_ror:8 row_mask:0xf bank_mask:0xf bound_ctrl:1
	ds_read_b128 v[220:223], v42 offset:19456
	ds_read_b128 v[236:239], v42 offset:11264
	v_add_f32_dpp v90, v90, v90 row_ror:4 row_mask:0xf bank_mask:0xf bound_ctrl:1
	v_pk_mul_f32 v[104:105], v[12:13], v[104:105]
	v_pk_fma_f32 v[104:105], v[10:11], v[106:107], v[104:105]
	v_add_f32_dpp v90, v90, v90 row_ror:2 row_mask:0xf bank_mask:0xf bound_ctrl:1
	v_add_f32_e32 v190, v104, v105
	ds_read_b128 v[104:107], v42 offset:2816
	v_add_f32_dpp v90, v90, v90 row_ror:1 row_mask:0xf bank_mask:0xf bound_ctrl:1
	v_pk_fma_f32 v[92:93], v[90:91], v[244:245], v[92:93] op_sel_hi:[0,1,1]
	v_pk_fma_f32 v[94:95], v[90:91], v[246:247], v[94:95] op_sel_hi:[0,1,1]
	ds_read_b128 v[244:247], v42 offset:23552
	v_pk_fma_f32 v[12:13], v[12:13], v[228:229], v[92:93]
	v_pk_fma_f32 v[10:11], v[10:11], v[230:231], v[94:95]
	ds_read_b128 v[228:231], v42 offset:7168
	s_waitcnt lgkmcnt(5)
	v_pk_mul_f32 v[88:89], v[12:13], v[224:225]
	v_pk_fma_f32 v[88:89], v[10:11], v[226:227], v[88:89]
	v_add_f32_e32 v90, v88, v89
	v_pk_mul_f32 v[92:93], v[110:111], v[240:241] op_sel:[1,0] op_sel_hi:[1,1]
	v_pk_mul_f32 v[94:95], v[110:111], v[242:243] op_sel:[1,0] op_sel_hi:[1,1]
	v_add_f32_dpp v90, v90, v90 row_ror:8 row_mask:0xf bank_mask:0xf bound_ctrl:1
	ds_read_b128 v[224:227], v42 offset:19712
	ds_read_b128 v[240:243], v42 offset:11520
	v_add_f32_dpp v90, v90, v90 row_ror:4 row_mask:0xf bank_mask:0xf bound_ctrl:1
	v_pk_mul_f32 v[100:101], v[12:13], v[100:101]
	v_pk_fma_f32 v[100:101], v[10:11], v[102:103], v[100:101]
	v_add_f32_dpp v90, v90, v90 row_ror:2 row_mask:0xf bank_mask:0xf bound_ctrl:1
	v_add_f32_e32 v191, v100, v101
	ds_read_b128 v[100:103], v42 offset:3072
	v_add_f32_dpp v90, v90, v90 row_ror:1 row_mask:0xf bank_mask:0xf bound_ctrl:1
	ds_read2st64_b32 v[110:111], v41 offset0:14 offset1:15
	v_pk_fma_f32 v[92:93], v[90:91], v[248:249], v[92:93] op_sel_hi:[0,1,1]
	v_pk_fma_f32 v[94:95], v[90:91], v[250:251], v[94:95] op_sel_hi:[0,1,1]
	ds_read_b128 v[248:251], v42 offset:23808
	v_pk_fma_f32 v[12:13], v[12:13], v[232:233], v[92:93]
	v_pk_fma_f32 v[10:11], v[10:11], v[234:235], v[94:95]
	ds_read_b128 v[232:235], v42 offset:7424
	s_waitcnt lgkmcnt(6)
	v_pk_mul_f32 v[88:89], v[12:13], v[220:221]
	v_pk_fma_f32 v[88:89], v[10:11], v[222:223], v[88:89]
	v_add_f32_e32 v90, v88, v89
	v_pk_mul_f32 v[92:93], v[108:109], v[236:237] op_sel_hi:[0,1]
	v_pk_mul_f32 v[94:95], v[108:109], v[238:239] op_sel_hi:[0,1]
	v_add_f32_dpp v90, v90, v90 row_ror:8 row_mask:0xf bank_mask:0xf bound_ctrl:1
	ds_read_b128 v[220:223], v42 offset:19968
	ds_read_b128 v[236:239], v42 offset:11776
	v_add_f32_dpp v90, v90, v90 row_ror:4 row_mask:0xf bank_mask:0xf bound_ctrl:1
	v_pk_mul_f32 v[104:105], v[12:13], v[104:105]
	v_pk_fma_f32 v[104:105], v[10:11], v[106:107], v[104:105]
	v_add_f32_dpp v90, v90, v90 row_ror:2 row_mask:0xf bank_mask:0xf bound_ctrl:1
	v_add_f32_e32 v200, v104, v105
	ds_read_b128 v[104:107], v42 offset:3328
	v_add_f32_dpp v90, v90, v90 row_ror:1 row_mask:0xf bank_mask:0xf bound_ctrl:1
	v_pk_fma_f32 v[92:93], v[90:91], v[244:245], v[92:93] op_sel_hi:[0,1,1]
	v_pk_fma_f32 v[94:95], v[90:91], v[246:247], v[94:95] op_sel_hi:[0,1,1]
	ds_read_b128 v[244:247], v42 offset:24064
	v_pk_fma_f32 v[12:13], v[12:13], v[228:229], v[92:93]
	v_pk_fma_f32 v[10:11], v[10:11], v[230:231], v[94:95]
	ds_read_b128 v[228:231], v42 offset:7680
	s_waitcnt lgkmcnt(5)
	v_pk_mul_f32 v[88:89], v[12:13], v[224:225]
	v_pk_fma_f32 v[88:89], v[10:11], v[226:227], v[88:89]
	v_add_f32_e32 v90, v88, v89
	v_pk_mul_f32 v[92:93], v[108:109], v[240:241] op_sel:[1,0] op_sel_hi:[1,1]
	v_pk_mul_f32 v[94:95], v[108:109], v[242:243] op_sel:[1,0] op_sel_hi:[1,1]
	v_add_f32_dpp v90, v90, v90 row_ror:8 row_mask:0xf bank_mask:0xf bound_ctrl:1
	ds_read_b128 v[224:227], v42 offset:20224
	ds_read_b128 v[240:243], v42 offset:12032
	v_add_f32_dpp v90, v90, v90 row_ror:4 row_mask:0xf bank_mask:0xf bound_ctrl:1
	v_pk_mul_f32 v[100:101], v[12:13], v[100:101]
	v_pk_fma_f32 v[100:101], v[10:11], v[102:103], v[100:101]
	v_add_f32_dpp v90, v90, v90 row_ror:2 row_mask:0xf bank_mask:0xf bound_ctrl:1
	v_add_f32_e32 v75, v100, v101
	ds_read_b128 v[100:103], v42 offset:3584
	v_add_f32_dpp v90, v90, v90 row_ror:1 row_mask:0xf bank_mask:0xf bound_ctrl:1
	v_pk_fma_f32 v[92:93], v[90:91], v[248:249], v[92:93] op_sel_hi:[0,1,1]
	v_pk_fma_f32 v[94:95], v[90:91], v[250:251], v[94:95] op_sel_hi:[0,1,1]
	ds_read_b128 v[248:251], v42 offset:24320
	v_pk_fma_f32 v[12:13], v[12:13], v[232:233], v[92:93]
	v_pk_fma_f32 v[10:11], v[10:11], v[234:235], v[94:95]
	ds_read_b128 v[232:235], v42 offset:7936
	s_waitcnt lgkmcnt(5)
	v_pk_mul_f32 v[88:89], v[12:13], v[220:221]
	v_pk_fma_f32 v[88:89], v[10:11], v[222:223], v[88:89]
	v_add_f32_e32 v90, v88, v89
	v_pk_mul_f32 v[92:93], v[110:111], v[236:237] op_sel_hi:[0,1]
	v_pk_mul_f32 v[94:95], v[110:111], v[238:239] op_sel_hi:[0,1]
	v_add_f32_dpp v90, v90, v90 row_ror:8 row_mask:0xf bank_mask:0xf bound_ctrl:1
	s_nop 1
	v_add_f32_dpp v90, v90, v90 row_ror:4 row_mask:0xf bank_mask:0xf bound_ctrl:1
	v_pk_mul_f32 v[104:105], v[12:13], v[104:105]
	v_pk_fma_f32 v[104:105], v[10:11], v[106:107], v[104:105]
	v_add_f32_dpp v90, v90, v90 row_ror:2 row_mask:0xf bank_mask:0xf bound_ctrl:1
	v_add_f32_e32 v80, v104, v105
	ds_read_b128 v[104:107], v42 offset:3840
	v_add_f32_dpp v90, v90, v90 row_ror:1 row_mask:0xf bank_mask:0xf bound_ctrl:1
	v_pk_fma_f32 v[92:93], v[90:91], v[244:245], v[92:93] op_sel_hi:[0,1,1]
	v_pk_fma_f32 v[94:95], v[90:91], v[246:247], v[94:95] op_sel_hi:[0,1,1]
	v_pk_fma_f32 v[12:13], v[12:13], v[228:229], v[92:93]
	v_pk_fma_f32 v[10:11], v[10:11], v[230:231], v[94:95]
	s_waitcnt lgkmcnt(1)
	v_pk_mul_f32 v[88:89], v[12:13], v[224:225]
	v_pk_fma_f32 v[88:89], v[10:11], v[226:227], v[88:89]
	v_add_f32_e32 v90, v88, v89
	v_pk_mul_f32 v[92:93], v[110:111], v[240:241] op_sel:[1,0] op_sel_hi:[1,1]
	v_pk_mul_f32 v[94:95], v[110:111], v[242:243] op_sel:[1,0] op_sel_hi:[1,1]
	v_add_f32_dpp v90, v90, v90 row_ror:8 row_mask:0xf bank_mask:0xf bound_ctrl:1
	s_nop 1
	v_add_f32_dpp v90, v90, v90 row_ror:4 row_mask:0xf bank_mask:0xf bound_ctrl:1
	v_pk_mul_f32 v[100:101], v[12:13], v[100:101]
	v_pk_fma_f32 v[100:101], v[10:11], v[102:103], v[100:101]
	v_add_f32_dpp v90, v90, v90 row_ror:2 row_mask:0xf bank_mask:0xf bound_ctrl:1
	v_add_f32_e32 v81, v100, v101
	s_nop 0
	v_add_f32_dpp v90, v90, v90 row_ror:1 row_mask:0xf bank_mask:0xf bound_ctrl:1
	v_pk_fma_f32 v[92:93], v[90:91], v[248:249], v[92:93] op_sel_hi:[0,1,1]
	v_pk_fma_f32 v[94:95], v[90:91], v[250:251], v[94:95] op_sel_hi:[0,1,1]
	v_pk_fma_f32 v[12:13], v[12:13], v[232:233], v[92:93]
	v_pk_fma_f32 v[10:11], v[10:11], v[234:235], v[94:95]
	s_waitcnt lgkmcnt(0)
	v_pk_mul_f32 v[104:105], v[12:13], v[104:105]
	v_pk_fma_f32 v[104:105], v[10:11], v[106:107], v[104:105]
	v_add_f32_dpp v96, v96, v96 row_mirror row_mask:0xf bank_mask:0x3
	v_add_f32_dpp v96, v187, v187 row_mirror row_mask:0xf bank_mask:0xc
	v_add_f32_e32 v82, v104, v105
	v_add_f32_dpp v97, v97, v97 row_mirror row_mask:0xf bank_mask:0x3
	v_add_f32_dpp v97, v190, v190 row_mirror row_mask:0xf bank_mask:0xc
	v_add_f32_dpp v98, v98, v98 row_mirror row_mask:0xf bank_mask:0x3
	v_add_f32_dpp v98, v191, v191 row_mirror row_mask:0xf bank_mask:0xc
	v_add_f32_dpp v99, v99, v99 row_mirror row_mask:0xf bank_mask:0x3
	v_add_f32_dpp v99, v200, v200 row_mirror row_mask:0xf bank_mask:0xc
	v_add_f32_dpp v87, v87, v87 row_mirror row_mask:0xf bank_mask:0x3
	v_add_f32_dpp v87, v75, v75 row_mirror row_mask:0xf bank_mask:0xc
	v_add_f32_dpp v217, v217, v217 row_mirror row_mask:0xf bank_mask:0x3
	v_add_f32_dpp v217, v80, v80 row_mirror row_mask:0xf bank_mask:0xc
	v_add_f32_dpp v218, v218, v218 row_mirror row_mask:0xf bank_mask:0x3
	v_add_f32_dpp v218, v81, v81 row_mirror row_mask:0xf bank_mask:0xc
	v_add_f32_dpp v219, v219, v219 row_mirror row_mask:0xf bank_mask:0x3
	v_add_f32_dpp v219, v82, v82 row_mirror row_mask:0xf bank_mask:0xc
	v_add_f32_dpp v96, v96, v96 row_half_mirror row_mask:0xf bank_mask:0x5
	v_add_f32_dpp v96, v87, v87 row_half_mirror row_mask:0xf bank_mask:0xa
	v_add_f32_dpp v97, v97, v97 row_half_mirror row_mask:0xf bank_mask:0x5
	v_add_f32_dpp v97, v217, v217 row_half_mirror row_mask:0xf bank_mask:0xa
	v_add_f32_dpp v98, v98, v98 row_half_mirror row_mask:0xf bank_mask:0x5
	v_add_f32_dpp v98, v218, v218 row_half_mirror row_mask:0xf bank_mask:0xa
	v_add_f32_dpp v99, v99, v99 row_half_mirror row_mask:0xf bank_mask:0x5
	v_add_f32_dpp v99, v219, v219 row_half_mirror row_mask:0xf bank_mask:0xa
	s_mov_b32 vcc_lo, 0xcccccccc
	s_mov_b32 vcc_hi, 0xcccccccc
	v_cndmask_b32_e32 v187, v96, v98, vcc
	v_cndmask_b32_e32 v190, v98, v96, vcc
	v_cndmask_b32_e32 v200, v99, v97, vcc
	v_cndmask_b32_e32 v191, v97, v99, vcc
	v_add_f32_dpp v75, v190, v187 quad_perm:[2,3,0,1] row_mask:0xf bank_mask:0xf bound_ctrl:1
	v_add_f32_dpp v80, v200, v191 quad_perm:[2,3,0,1] row_mask:0xf bank_mask:0xf bound_ctrl:1
	s_mov_b32 vcc_lo, 0xaaaaaaaa
	s_mov_b32 vcc_hi, 0xaaaaaaaa
	v_cndmask_b32_e32 v81, v75, v80, vcc
	v_cndmask_b32_e32 v82, v80, v75, vcc
	s_nop 1
	v_add_f32_dpp v87, v82, v81 quad_perm:[1,0,3,2] row_mask:0xf bank_mask:0xf bound_ctrl:1
	s_waitcnt vmcnt(7)
	v_cmp_gt_i32_e32 vcc, 0, v8
	v_cmp_gt_i32_e64 s[38:39], -2, v8
	v_cmp_gt_i32_e64 s[40:41], -3, v8
	v_cmp_gt_i32_e64 s[42:43], 0, v14
	v_cmp_gt_i32_e64 s[44:45], -2, v14
	v_cmp_gt_i32_e64 s[46:47], 1, v8
	v_cmp_gt_i32_e64 s[48:49], -1, v8
	v_cmp_gt_i32_e64 s[52:53], -1, v14
	v_lshl_or_b32 v8, s5, 4, v31
	v_cndmask_b32_e64 v82, v73, 0, s[42:43]
	v_cndmask_b32_e64 v81, v76, 0, s[42:43]
	v_cndmask_b32_e64 v76, v77, 0, s[52:53]
	v_cndmask_b32_e64 v77, v84, 0, s[52:53]
	v_cndmask_b32_e64 v73, v85, 0, s[44:45]
	v_or_b32_e32 v84, s56, v8
	v_mov_b32_e32 v85, s57
	v_cmp_gt_i32_e64 s[50:51], 1, v14
	v_cmp_gt_i32_e64 s[54:55], -3, v14
	v_lshlrev_b64 v[84:85], 10, v[84:85]
	s_add_i32 s5, s4, 2
	v_cndmask_b32_e64 v89, v59, 0, vcc
	v_cndmask_b32_e64 v88, v60, 0, vcc
	v_cndmask_b32_e64 v60, v67, 0, s[38:39]
	v_cndmask_b32_e64 v59, v68, 0, s[40:41]
	v_cndmask_b32_e64 v64, v64, 0, s[38:39]
	v_cndmask_b32_e64 v75, v69, 0, s[42:43]
	v_cndmask_b32_e64 v69, v78, 0, s[44:45]
	v_cndmask_b32_e64 v67, v57, 0, s[46:47]
	v_cndmask_b32_e64 v57, v62, 0, s[48:49]
	v_cndmask_b32_e64 v62, v55, 0, s[46:47]
	v_cndmask_b32_e64 v61, v61, 0, s[48:49]
	v_cndmask_b32_e64 v55, v66, 0, s[40:41]
	v_cndmask_b32_e64 v78, v72, 0, s[50:51]
	v_cndmask_b32_e64 v74, v74, 0, s[52:53]
	s_waitcnt vmcnt(5)
	v_cndmask_b32_e64 v14, v79, 0, s[54:55]
	v_cndmask_b32_e64 v66, v54, 0, s[46:47]
	v_cndmask_b32_e64 v68, v56, 0, vcc
	v_cndmask_b32_e64 v58, v58, 0, s[48:49]
	v_cndmask_b32_e64 v56, v63, 0, s[38:39]
	v_cndmask_b32_e64 v54, v65, 0, s[40:41]
	v_cndmask_b32_e64 v80, v70, 0, s[50:51]
	v_cndmask_b32_e64 v79, v71, 0, s[50:51]
	v_cndmask_b32_e64 v72, v83, 0, s[44:45]
	v_cndmask_b32_e64 v70, v0, 0, s[54:55]
	s_waitcnt vmcnt(4)
	v_cndmask_b32_e64 v71, v86, 0, s[54:55]
	v_cvt_pk_bf16_f32 v0, v87, s0
	v_lshl_add_u64 v[84:85], v[6:7], 0, v[84:85]
	s_cmpk_lt_u32 s4, 0xfe
	s_mov_b32 s4, s5
	global_store_short v[84:85], v0, off
	s_cbranch_scc1 .LBB0_334
	s_setprio 0
	v_mov_b32_e32 v0, v133
	s_barrier
	s_nop 0
	v_cmp_eq_u32_e32 vcc, 0, v0
	s_and_saveexec_b64 s[4:5], vcc
	s_cbranch_execnz .LBB0_329
	s_branch .LBB0_332
